# 7b + the per-unit vmcnt(0) of the mini-GEMM unit loops hoisted in front of the loops (later units no longer wait for store acks)
# speedup vs baseline: 1.0134x; 1.0035x over previous
; #define LAS __attribute__((address_space(3)))
; template <int MODE> __device__ __forceinline__ void mini_gemm_ctx(const u16* A, const u16* Bt, int N, int K, u16* Ob, int ldo, int act, const float* gate, LAS unsigned char* L, int vb, int G_, int wave, int lane) {
;     const int ncg = (N + 63) >> 6, ntiles = 8 * ncg, kslice = K >> 3;
;     const int fr = lane & 15, fq = lane >> 4;
;     LAS f32x4* red = (LAS f32x4*)L;
;     for (int tile = vb; tile < ntiles; tile += G_) {
;         const int r0 = (tile & 7) * 64, n0 = (tile >> 3) * 64;
;         f32x4 acc[4][4];
; #pragma unroll
;         for (int a = 0; a < 4; ++a)
; #pragma unroll
;             for (int c = 0; c < 4; ++c) acc[a][c] = (f32x4){0.f, 0.f, 0.f, 0.f};
;         const u16* ap = A + (size_t)(r0 + fr) * K + wave * kslice + 8 * fq; const u16* bp = Bt + (size_t)(n0 + fr) * K + wave * kslice + 8 * fq;
; __global__ void __launch_bounds__(512, 2) fwd_megakernel(Args args) {
;     ...
;             const u16* Aop = (ph == 9) ? HB : XNY; const int Kop = (ph == 9) ? FF_ : 1024;
;             const u16* Bop = (const u16*)(wl + (ph == 1 ? W_IN : ph == 8 ? W_1 : ph == 6 ? W_OUT : W_2));
;             const int Nmain = (ph == 1) ? NPAD : (ph == 8 ? FF_ : 1024), Nctx = Nmain;
;             u16* Oop = (ph == 1) ? P : (ph == 8 ? HB : (ph == 6 ? (u16*)(ws + WS_YA) : XNY));
;             const float* gate = (ph == 6) ? modl + 2048 : (ph == 9 ? modl + 5120 : (const float*)nullptr);
;             if (ph == 1 || layer == 0) {
;                 if (gate) mini_gemm_ctx<1>(Aop + (size_t)M_LAT * Kop, Bop, Nctx, Kop, Oop + (size_t)M_LAT * Nmain, Nmain, 0, gate + 2 * 6144, L, vcu, G_, wave, lane);
;                 else mini_gemm_ctx<0>(Aop + (size_t)M_LAT * Kop, Bop, Nctx, Kop, Oop + (size_t)M_LAT * Nmain, Nmain, ph == 8 ? 1 : 0, nullptr, L, vcu, G_, wave, lane);
.LBB0_376:
	s_and_b64 vcc, exec, s[86:87]
	s_cbranch_vccz .LBB0_454
	v_readlane_b32 s4, v238, 33
	s_add_u32 s6, s4, 0x2000
	v_readlane_b32 s5, v238, 34
	s_addc_u32 s7, s5, 0
	s_add_u32 s10, s4, 0x5000
	s_addc_u32 s14, s5, 0
	s_cmp_eq_u32 s74, 9
	s_cselect_b64 s[22:23], -1, 0
	s_and_b64 s[4:5], s[22:23], exec
	s_movk_i32 s15, 0x1000
	s_cselect_b32 s27, s13, s37
	s_cselect_b32 s75, s12, s36
	s_cselect_b32 s82, s15, 0x400
	s_cselect_b32 s5, s14, 0
	s_cselect_b32 s4, s10, 0
	s_cselect_b32 s10, 12, 10
	s_cmp_eq_u32 s74, 6
	s_cselect_b32 s4, s6, s4
	s_cselect_b32 s5, s7, s5
	s_add_u32 s6, s58, 0x1ae00000
	s_addc_u32 s7, s59, 0
	s_cmp_eq_u32 s74, 6
	s_cselect_b32 s18, s6, s36
	s_cselect_b32 s19, s7, s37
	v_readlane_b32 s6, v238, 31
	v_readlane_b32 s7, v238, 32
	s_cselect_b32 s14, s2, 0xf00000
	s_and_b64 s[6:7], s[6:7], exec
	s_cselect_b32 s86, 0x1700000, 0
	s_cmp_eq_u32 s74, 8
	s_cselect_b64 s[38:39], -1, 0
	s_and_b64 s[6:7], s[38:39], exec
	s_cselect_b32 s28, 0x700000, s14
	s_cselect_b32 s29, s15, 0x400
	s_cmp_eq_u32 s74, 1
	s_cselect_b64 s[14:15], -1, 0
	s_and_b64 s[6:7], s[14:15], exec
	s_cselect_b32 s87, 0, s28
	s_cselect_b32 s76, 0xa00, s29
	s_or_b64 s[6:7], s[14:15], s[38:39]
	s_and_b64 s[6:7], s[6:7], exec
	s_cselect_b32 s7, s13, s19
	s_cselect_b32 s6, s12, s18
	v_readlane_b32 s12, v238, 28
	v_readlane_b32 s13, v238, 29
	s_or_b64 s[14:15], s[14:15], s[12:13]
	s_cmp_eq_u64 s[4:5], 0
	s_cselect_b64 s[40:41], -1, 0
	s_cmp_lg_u64 s[4:5], 0
	s_cselect_b64 s[12:13], -1, 0
	s_andn2_b64 vcc, exec, s[14:15]
	s_cbranch_vccnz .LBB0_399
	s_lshl_b32 s14, s76, 16
	s_add_u32 s18, s6, s14
	s_addc_u32 s19, s7, 0
	s_lshr_b32 s79, s76, 3
	s_lshr_b32 s80, s82, 3
	s_cmp_lt_i32 s84, s79
	s_cselect_b64 s[28:29], -1, 0
	s_and_b64 s[14:15], s[22:23], exec
	s_cselect_b32 s14, 9, 7
	s_lshl_b32 s34, s54, s14
	v_lshrrev_b32_e32 v0, 2, v224
	s_ashr_i32 s35, s34, 31
	s_lshl_b32 s81, s54, 14
	s_lshl_b32 s30, s54, 1
	s_lshl_b32 s14, s54, 3
	v_and_b32_e32 v0, 12, v0
	s_lshl_b32 s88, s82, 5
	v_and_or_b32 v86, s14, -16, v0
	s_and_b64 s[14:15], s[22:23], exec
	s_mov_b32 s14, 0x30000
	v_and_b32_e32 v84, 15, v225
	s_cselect_b32 s89, s14, 0xc000
	s_lshl_b32 s14, s54, 5
	v_and_or_b32 v87, s14, 32, v84
	s_or_b32 s14, s30, 1
	v_lshl_add_u32 v85, v224, 4, 0
	s_lshl_b32 s15, s14, 4
	v_lshl_add_u32 v88, s54, 11, v85
	v_and_or_b32 v93, s15, 48, v84
	v_lshl_add_u32 v94, s14, 10, v85
	s_and_b64 s[14:15], s[22:23], exec
	v_cndmask_b32_e64 v0, 0, 1, s[28:29]
	v_add_u32_e32 v89, 0x10000, v88
	v_add_u32_e32 v90, 0x14000, v88
	v_add_u32_e32 v91, 0x18000, v88
	v_add_u32_e32 v92, 0x1c000, v88
	v_add_u32_e32 v95, 0x10000, v94
	v_add_u32_e32 v96, 0x14000, v94
	v_add_u32_e32 v97, 0x18000, v94
	v_add_u32_e32 v98, 0x1c000, v94
	s_cselect_b32 s83, 12, 10
	s_mov_b64 s[14:15], -1
	s_andn2_b64 vcc, exec, s[12:13]
	v_cmp_ne_u32_e64 s[42:43], 1, v0
	s_cbranch_vccnz .LBB0_389
	s_and_b64 vcc, exec, s[42:43]
	s_cbranch_vccnz .LBB0_388
	s_add_u32 s36, s4, 0xc000
	s_addc_u32 s37, s5, 0
	s_add_u32 s14, s87, s86
	s_addc_u32 s15, 0, 0
	s_lshl_b64 s[30:31], s[34:35], 1
	s_add_u32 s44, s14, s30
	s_addc_u32 s45, s15, s31
	s_add_u32 s48, s58, s44
	s_addc_u32 s49, s59, s45
	s_lshl_b32 s46, s89, 1
	s_add_u32 s14, s44, s46
	s_addc_u32 s15, s45, 0
	s_add_u32 s60, s58, s14
	s_addc_u32 s61, s59, s15
	s_mul_i32 s14, s82, 0x10020
	s_add_u32 s62, s75, s14
	s_addc_u32 s63, s27, 0
	s_mul_i32 s14, s82, 0x10040
	s_add_u32 s14, s75, s14
	s_addc_u32 s15, s27, 0
	s_lshl_b32 s28, s82, 6
	s_add_u32 s28, s44, s28
	s_addc_u32 s29, s45, 0
	s_add_u32 s28, s58, s28
	s_addc_u32 s29, s59, s29
	s_lshl_b32 s47, s82, 16
	s_add_u32 s47, s47, s30
	s_addc_u32 s50, 0, s31
	s_add_u32 s30, s47, s46
	s_addc_u32 s31, s50, 0
	s_add_u32 s30, s75, s30
	s_addc_u32 s31, s27, s31
	s_add_u32 s46, s75, s47
	s_addc_u32 s47, s27, s50
	s_add_u32 s72, s46, 64
	s_addc_u32 s73, s47, 0
	s_add_u32 s44, s44, s88
	s_addc_u32 s45, s45, 0
	s_add_u32 s54, s58, s44
	s_waitcnt vmcnt(3)
	v_and_b32_e32 v66, 48, v225
	v_mov_b32_e32 v67, v1
	s_addc_u32 s55, s59, s45
	v_readlane_b32 s84, v238, 4
	s_waitcnt vmcnt(0)
	s_branch .LBB0_382

; template <int MODE> __device__ __forceinline__ void mini_gemm_ctx(const u16* A, const u16* Bt, int N, int K, u16* Ob, int ldo, int act, const float* gate, LAS unsigned char* L, int vb, int G_, int wave, int lane) {
;     ...
;     for (int tile = vb; tile < ntiles; tile += G_) {
;         const int r0 = (tile & 7) * 64, n0 = (tile >> 3) * 64;
;         f32x4 acc[4][4];
; #pragma unroll
;         for (int a = 0; a < 4; ++a)
; #pragma unroll
;             for (int c = 0; c < 4; ++c) acc[a][c] = (f32x4){0.f, 0.f, 0.f, 0.f};
;         const u16* ap = A + (size_t)(r0 + fr) * K + wave * kslice + 8 * fq; const u16* bp = Bt + (size_t)(n0 + fr) * K + wave * kslice + 8 * fq;
.LBB0_382:
	s_lshl_b32 s85, s84, 3
	s_lshl_b32 s44, s84, 6
	s_andn2_b32 s85, s85, 63
	s_and_b32 s77, s44, 0x1c0
	v_or_b32_e32 v2, s85, v84
	v_or_b32_e32 v0, s77, v84
	v_ashrrev_i32_e32 v3, 31, v2
	v_lshlrev_b32_e32 v0, s10, v0
	v_lshlrev_b64 v[2:3], s83, v[2:3]
	v_lshlrev_b64 v[2:3], 1, v[2:3]
	v_lshl_add_u64 v[4:5], s[34:35], 0, v[0:1]
	v_lshl_add_u64 v[68:69], s[48:49], 0, v[2:3]
	v_lshl_add_u64 v[70:71], s[60:61], 0, v[2:3]
	v_lshlrev_b64 v[4:5], 1, v[4:5]
	v_lshl_add_u64 v[76:77], s[28:29], 0, v[2:3]
	v_lshlrev_b32_e32 v0, 1, v0
	v_lshl_add_u64 v[82:83], s[54:55], 0, v[2:3]
	v_mov_b32_e32 v2, 0
	v_lshl_add_u64 v[72:73], s[62:63], 0, v[4:5]
	v_lshl_add_u64 v[74:75], s[14:15], 0, v[4:5]
	v_lshl_add_u64 v[78:79], s[30:31], 0, v[0:1]
	v_lshl_add_u64 v[80:81], s[72:73], 0, v[0:1]
	s_mov_b32 s78, 0
	v_mov_b32_e32 v3, v2
	v_mov_b32_e32 v4, v2
	v_mov_b32_e32 v5, v2
	v_mov_b32_e32 v6, v2
	v_mov_b32_e32 v7, v2
	v_mov_b32_e32 v8, v2
	v_mov_b32_e32 v9, v2
	v_mov_b32_e32 v10, v2
	v_mov_b32_e32 v11, v2
	v_mov_b32_e32 v12, v2
	v_mov_b32_e32 v13, v2
	v_mov_b32_e32 v14, v2
	v_mov_b32_e32 v15, v2
	v_mov_b32_e32 v16, v2
	v_mov_b32_e32 v17, v2
	v_mov_b32_e32 v18, v2
	v_mov_b32_e32 v19, v2
	v_mov_b32_e32 v20, v2
	v_mov_b32_e32 v21, v2
	v_mov_b32_e32 v22, v2
	v_mov_b32_e32 v23, v2
	v_mov_b32_e32 v24, v2
	v_mov_b32_e32 v25, v2
	v_mov_b32_e32 v26, v2
	v_mov_b32_e32 v27, v2
	v_mov_b32_e32 v28, v2
	v_mov_b32_e32 v29, v2
	v_mov_b32_e32 v30, v2
	v_mov_b32_e32 v31, v2
	v_mov_b32_e32 v32, v2
	v_mov_b32_e32 v33, v2
	v_mov_b32_e32 v34, v2
	v_mov_b32_e32 v35, v2
	v_mov_b32_e32 v36, v2
	v_mov_b32_e32 v37, v2
	v_mov_b32_e32 v38, v2
	v_mov_b32_e32 v39, v2
	v_mov_b32_e32 v40, v2
	v_mov_b32_e32 v41, v2
	v_mov_b32_e32 v42, v2
	v_mov_b32_e32 v43, v2
	v_mov_b32_e32 v44, v2
	v_mov_b32_e32 v45, v2
	v_mov_b32_e32 v46, v2
	v_mov_b32_e32 v47, v2
	v_mov_b32_e32 v48, v2
	v_mov_b32_e32 v49, v2
	v_mov_b32_e32 v50, v2
	v_mov_b32_e32 v51, v2
	v_mov_b32_e32 v52, v2
	v_mov_b32_e32 v53, v2
	v_mov_b32_e32 v54, v2
	v_mov_b32_e32 v55, v2
	v_mov_b32_e32 v56, v2
	v_mov_b32_e32 v57, v2
	v_mov_b32_e32 v62, v2
	v_mov_b32_e32 v63, v2
	v_mov_b32_e32 v64, v2
	v_mov_b32_e32 v65, v2
	v_mov_b32_e32 v58, v2
	v_mov_b32_e32 v59, v2
	v_mov_b32_e32 v60, v2
	v_mov_b32_e32 v61, v2

; #define LAS __attribute__((address_space(3)))
; template <int MODE> __device__ __forceinline__ void mini_gemm_ctx(const u16* A, const u16* Bt, int N, int K, u16* Ob, int ldo, int act, const float* gate, LAS unsigned char* L, int vb, int G_, int wave, int lane) {
;     const int ncg = (N + 63) >> 6, ntiles = 8 * ncg, kslice = K >> 3;
;     const int fr = lane & 15, fq = lane >> 4;
;     LAS f32x4* red = (LAS f32x4*)L;
;     for (int tile = vb; tile < ntiles; tile += G_) {
;         const int r0 = (tile & 7) * 64, n0 = (tile >> 3) * 64;
;         f32x4 acc[4][4];
; #pragma unroll
;         for (int a = 0; a < 4; ++a)
; #pragma unroll
;             for (int c = 0; c < 4; ++c) acc[a][c] = (f32x4){0.f, 0.f, 0.f, 0.f};
;         const u16* ap = A + (size_t)(r0 + fr) * K + wave * kslice + 8 * fq; const u16* bp = Bt + (size_t)(n0 + fr) * K + wave * kslice + 8 * fq;
.LBB0_389:
	s_andn2_b64 vcc, exec, s[14:15]
	s_cbranch_vccnz .LBB0_399
	s_and_b64 vcc, exec, s[42:43]
	s_cbranch_vccnz .LBB0_399
	s_add_u32 s14, s87, s86
	s_addc_u32 s15, 0, 0
	s_lshl_b64 s[42:43], s[34:35], 1
	s_add_u32 s44, s14, s42
	s_addc_u32 s45, s15, s43
	s_add_u32 s14, s58, s44
	s_addc_u32 s15, s59, s45
	s_lshl_b32 s46, s89, 1
	s_add_u32 s28, s44, s46
	s_addc_u32 s29, s45, 0
	s_add_u32 s28, s58, s28
	s_addc_u32 s29, s59, s29
	s_mul_i32 s30, s82, 0x10020
	s_add_u32 s30, s75, s30
	s_addc_u32 s31, s27, 0
	s_mul_i32 s36, s82, 0x10040
	s_add_u32 s36, s75, s36
	s_addc_u32 s37, s27, 0
	s_lshl_b32 s47, s82, 6
	s_add_u32 s47, s44, s47
	s_addc_u32 s49, s45, 0
	s_add_u32 s48, s58, s47
	s_addc_u32 s49, s59, s49
	s_lshl_b32 s47, s82, 16
	s_add_u32 s42, s47, s42
	s_addc_u32 s43, 0, s43
	s_add_u32 s46, s42, s46
	s_addc_u32 s47, s43, 0
	s_add_u32 s50, s75, s46
	s_addc_u32 s51, s27, s47
	s_add_u32 s42, s75, s42
	s_addc_u32 s43, s27, s43
	s_add_u32 s54, s42, 64
	s_addc_u32 s55, s43, 0
	s_add_u32 s42, s44, s88
	s_addc_u32 s43, s45, 0
	s_add_u32 s60, s58, s42
	s_waitcnt vmcnt(3)
	v_and_b32_e32 v66, 48, v225
	v_mov_b32_e32 v67, v1
	s_addc_u32 s61, s59, s43
	s_mov_b32 s62, s84
	s_waitcnt vmcnt(0)
	s_branch .LBB0_393

; template <int MODE> __device__ __forceinline__ void mini_gemm_ctx(const u16* A, const u16* Bt, int N, int K, u16* Ob, int ldo, int act, const float* gate, LAS unsigned char* L, int vb, int G_, int wave, int lane) {
;     ...
;     for (int tile = vb; tile < ntiles; tile += G_) {
;         const int r0 = (tile & 7) * 64, n0 = (tile >> 3) * 64;
;         f32x4 acc[4][4];
; #pragma unroll
;         for (int a = 0; a < 4; ++a)
; #pragma unroll
;             for (int c = 0; c < 4; ++c) acc[a][c] = (f32x4){0.f, 0.f, 0.f, 0.f};
;         const u16* ap = A + (size_t)(r0 + fr) * K + wave * kslice + 8 * fq; const u16* bp = Bt + (size_t)(n0 + fr) * K + wave * kslice + 8 * fq;
.LBB0_393:
	s_lshl_b32 s63, s62, 3
	s_lshl_b32 s42, s62, 6
	s_andn2_b32 s63, s63, 63
	s_and_b32 s72, s42, 0x1c0
	v_or_b32_e32 v2, s63, v84
	v_or_b32_e32 v0, s72, v84
	v_ashrrev_i32_e32 v3, 31, v2
	v_lshlrev_b32_e32 v0, s10, v0
	v_lshlrev_b64 v[2:3], s83, v[2:3]
	v_lshlrev_b64 v[2:3], 1, v[2:3]
	v_lshl_add_u64 v[4:5], s[34:35], 0, v[0:1]
	v_lshl_add_u64 v[68:69], s[14:15], 0, v[2:3]
	v_lshl_add_u64 v[70:71], s[28:29], 0, v[2:3]
	v_lshlrev_b64 v[4:5], 1, v[4:5]
	v_lshl_add_u64 v[76:77], s[48:49], 0, v[2:3]
	v_lshlrev_b32_e32 v0, 1, v0
	v_lshl_add_u64 v[82:83], s[60:61], 0, v[2:3]
	v_mov_b32_e32 v2, 0
	v_lshl_add_u64 v[72:73], s[30:31], 0, v[4:5]
	v_lshl_add_u64 v[74:75], s[36:37], 0, v[4:5]
	v_lshl_add_u64 v[78:79], s[50:51], 0, v[0:1]
	v_lshl_add_u64 v[80:81], s[54:55], 0, v[0:1]
	s_mov_b32 s73, 0
	v_mov_b32_e32 v3, v2
	v_mov_b32_e32 v4, v2
	v_mov_b32_e32 v5, v2
	v_mov_b32_e32 v6, v2
	v_mov_b32_e32 v7, v2
	v_mov_b32_e32 v8, v2
	v_mov_b32_e32 v9, v2
	v_mov_b32_e32 v10, v2
	v_mov_b32_e32 v11, v2
	v_mov_b32_e32 v12, v2
	v_mov_b32_e32 v13, v2
	v_mov_b32_e32 v14, v2
	v_mov_b32_e32 v15, v2
	v_mov_b32_e32 v16, v2
	v_mov_b32_e32 v17, v2
	v_mov_b32_e32 v18, v2
	v_mov_b32_e32 v19, v2
	v_mov_b32_e32 v20, v2
	v_mov_b32_e32 v21, v2
	v_mov_b32_e32 v22, v2
	v_mov_b32_e32 v23, v2
	v_mov_b32_e32 v24, v2
	v_mov_b32_e32 v25, v2
	v_mov_b32_e32 v26, v2
	v_mov_b32_e32 v27, v2
	v_mov_b32_e32 v28, v2
	v_mov_b32_e32 v29, v2
	v_mov_b32_e32 v30, v2
	v_mov_b32_e32 v31, v2
	v_mov_b32_e32 v32, v2
	v_mov_b32_e32 v33, v2
	v_mov_b32_e32 v34, v2
	v_mov_b32_e32 v35, v2
	v_mov_b32_e32 v36, v2
	v_mov_b32_e32 v37, v2
	v_mov_b32_e32 v38, v2
	v_mov_b32_e32 v39, v2
	v_mov_b32_e32 v40, v2
	v_mov_b32_e32 v41, v2
	v_mov_b32_e32 v42, v2
	v_mov_b32_e32 v43, v2
	v_mov_b32_e32 v44, v2
	v_mov_b32_e32 v45, v2
	v_mov_b32_e32 v46, v2
	v_mov_b32_e32 v47, v2
	v_mov_b32_e32 v48, v2
	v_mov_b32_e32 v49, v2
	v_mov_b32_e32 v50, v2
	v_mov_b32_e32 v51, v2
	v_mov_b32_e32 v52, v2
	v_mov_b32_e32 v53, v2
	v_mov_b32_e32 v54, v2
	v_mov_b32_e32 v55, v2
	v_mov_b32_e32 v56, v2
	v_mov_b32_e32 v57, v2
	v_mov_b32_e32 v62, v2
	v_mov_b32_e32 v63, v2
	v_mov_b32_e32 v64, v2
	v_mov_b32_e32 v65, v2
	v_mov_b32_e32 v58, v2
	v_mov_b32_e32 v59, v2
	v_mov_b32_e32 v60, v2
	v_mov_b32_e32 v61, v2
